# L1 in-proj epilogue: 8 ssq loads hoisted to epilogue start (one drain instead of 8)
# speedup vs baseline: 1.0642x; 1.0642x over previous
; __device__ __forceinline__ v4u pack8(const float (&y)[8]) { return (v4u){pk2(y[0], y[1]), pk2(y[2], y[3]), pk2(y[4], y[5]), pk2(y[6], y[7])}; }
;     __device__ __forceinline__ void operator()(const f32x4 (&acc)[2][2][4][2], const pg8::Unit& u, int wr, int wc, int fr, int fq) const {
;     ...
;             const bool gate = (u.pn >= 36);
; #pragma unroll
;             for (int ai = 0; ai < 2; ++ai)
; #pragma unroll
;                 for (int m = 0; m < 4; ++m) {
;                     const int lrow = lrow0 + ai * 128 + m * 16; const int row = row_base + lrow;
;                     const float rs = rsqrtf(ssq[row] * (1.f / 1024.f) + EPS);
; #pragma unroll
;                     for (int bj = 0; bj < 2; ++bj) {
;                         const int c = cb + bj * 128;
;                         const f32x4 v0 = acc[ai][bj][m][0] * rs, v1 = acc[ai][bj][m][1] * rs;
;                         const float v[8] = {v0[0], v0[1], v0[2], v0[3], v1[0], v1[1], v1[2], v1[3]};
;                         if (!gate) *(v4u*)(o0 + (size_t)lrow * 9216 + u.pn * 256 + c) = pack8(v);
.LBB0_129:
	v_lshl_add_u32 v182, s25, 8, v1
	v_add_u32_e32 v178, s41, v182
	v_readlane_b32 s46, v251, 29
	v_ashrrev_i32_e32 v179, 31, v178
	v_readlane_b32 s47, v251, 30
	s_cmp_lt_i32 s24, 36
	s_movk_i32 s13, 0x4800
	v_lshl_add_u64 v[150:151], v[178:179], 2, s[46:47]
	global_load_dword v196, v[150:151], off offset:64
	global_load_dword v197, v[150:151], off offset:128
	global_load_dword v198, v[150:151], off offset:192
	global_load_dword v199, v[150:151], off offset:512
	global_load_dword v200, v[150:151], off offset:576
	global_load_dword v201, v[150:151], off offset:640
	global_load_dword v202, v[150:151], off offset:704
	global_load_dword v150, v[150:151], off
	s_cselect_b64 s[2:3], -1, 0
	s_lshl_b32 s24, s24, 8
	s_ashr_i32 s25, s24, 31
	v_readlane_b32 s20, v255, 24
	v_readlane_b32 s21, v255, 25
	s_waitcnt vmcnt(0)
	v_fmamk_f32 v150, v150, 0x3a800000, v139
	v_cmp_gt_f32_e32 vcc, s33, v150
	v_mul_f32_e32 v151, 0x4b800000, v150
	s_nop 0
	v_cndmask_b32_e32 v150, v150, v151, vcc
	v_rsq_f32_e32 v150, v150
	s_nop 0
	v_mul_f32_e32 v151, 0x45800000, v150
	v_cndmask_b32_e32 v168, v150, v151, vcc
	v_mad_i64_i32 v[150:151], s[4:5], v182, s13, 0
	v_pk_mul_f32 v[174:175], v[128:129], v[168:169] op_sel_hi:[1,0]
	v_lshl_add_u64 v[128:129], s[34:35], 0, v[150:151]
	v_pk_mul_f32 v[176:177], v[126:127], v[168:169] op_sel_hi:[1,0]
	v_pk_mul_f32 v[126:127], v[124:125], v[168:169] op_sel_hi:[1,0]
	v_pk_mul_f32 v[172:173], v[122:123], v[168:169] op_sel_hi:[1,0]
	s_mov_b64 s[4:5], -1
	s_and_b64 vcc, exec, s[2:3]
	v_lshl_add_u64 v[170:171], s[24:25], 1, v[128:129]
	s_cbranch_vccz .LBB0_131
	v_cvt_pk_bf16_f32 v122, v176, v177
	v_cvt_pk_bf16_f32 v123, v174, v175
	v_cvt_pk_bf16_f32 v124, v172, v173
	v_cvt_pk_bf16_f32 v125, v126, v127
	v_lshl_add_u64 v[180:181], s[24:25], 1, v[128:129]
	s_mov_b64 s[4:5], 0

; __device__ __forceinline__ float silu_f(float x) { return x * __builtin_amdgcn_rcpf(1.f + __expf(-x)); }
; __device__ __forceinline__ v4u pack8(const float (&y)[8]) { return (v4u){pk2(y[0], y[1]), pk2(y[2], y[3]), pk2(y[4], y[5]), pk2(y[6], y[7])}; }
;     __device__ __forceinline__ void operator()(const f32x4 (&acc)[2][2][4][2], const pg8::Unit& u, int wr, int wc, int fr, int fq) const {
;     ...
;                     const int lrow = lrow0 + ai * 128 + m * 16; const int row = row_base + lrow;
;                     const float rs = rsqrtf(ssq[row] * (1.f / 1024.f) + EPS);
; #pragma unroll
;                     for (int bj = 0; bj < 2; ++bj) {
;                         const int c = cb + bj * 128;
;                         const f32x4 v0 = acc[ai][bj][m][0] * rs, v1 = acc[ai][bj][m][1] * rs;
;                         const float v[8] = {v0[0], v0[1], v0[2], v0[3], v1[0], v1[1], v1[2], v1[3]};
;                         if (!gate) *(v4u*)(o0 + (size_t)lrow * 9216 + u.pn * 256 + c) = pack8(v);
;                         else { float y[8];
; #pragma unroll
;                             for (int j = 0; j < 8; ++j) y[j] = silu_f(v[j]);
;                             *(v4u*)(Y + (size_t)row * 1024 + (u.pn - 36) * 256 + c) = pack8(y); }
.LBB0_137:
	v_mov_b32_e32 v127, v0
	v_lshl_add_u64 v[118:119], v[170:171], 0, v[126:127]
	global_store_dwordx4 v[118:119], v[114:117], off offset:256
	s_nop 1
	v_or_b32_e32 v116, 16, v182
	v_add_u32_e32 v122, s41, v116
	v_ashrrev_i32_e32 v123, 31, v122
	v_lshl_add_u64 v[114:115], v[122:123], 2, s[46:47]
	v_mov_b32_e32 v114, v196
	v_mad_i64_i32 v[116:117], s[2:3], v116, s13, 0
	s_mov_b64 s[2:3], -1
	v_fmamk_f32 v114, v114, 0x3a800000, v139
	v_cmp_gt_f32_e32 vcc, s33, v114
	v_mul_f32_e32 v115, 0x4b800000, v114
	s_nop 0
	v_cndmask_b32_e32 v114, v114, v115, vcc
	v_rsq_f32_e32 v114, v114
	s_nop 0
	v_mul_f32_e32 v115, 0x45800000, v114
	v_cndmask_b32_e32 v114, v114, v115, vcc
	v_pk_mul_f32 v[124:125], v[110:111], v[114:115] op_sel_hi:[1,0]
	v_lshl_add_u64 v[110:111], s[34:35], 0, v[116:117]
	v_pk_mul_f32 v[120:121], v[112:113], v[114:115] op_sel_hi:[1,0]
	v_pk_mul_f32 v[112:113], v[108:109], v[114:115] op_sel_hi:[1,0]
	v_pk_mul_f32 v[118:119], v[106:107], v[114:115] op_sel_hi:[1,0]
	s_and_b64 vcc, exec, s[4:5]
	v_lshl_add_u64 v[116:117], s[24:25], 1, v[110:111]
	s_cbranch_vccnz .LBB0_139
	v_cvt_pk_bf16_f32 v106, v124, v125
	v_cvt_pk_bf16_f32 v107, v120, v121
	v_cvt_pk_bf16_f32 v108, v118, v119
	v_cvt_pk_bf16_f32 v109, v112, v113
	v_lshl_add_u64 v[128:129], s[24:25], 1, v[110:111]
	s_mov_b64 s[2:3], 0

; __device__ __forceinline__ float silu_f(float x) { return x * __builtin_amdgcn_rcpf(1.f + __expf(-x)); }
; __device__ __forceinline__ v4u pack8(const float (&y)[8]) { return (v4u){pk2(y[0], y[1]), pk2(y[2], y[3]), pk2(y[4], y[5]), pk2(y[6], y[7])}; }
;     __device__ __forceinline__ void operator()(const f32x4 (&acc)[2][2][4][2], const pg8::Unit& u, int wr, int wc, int fr, int fq) const {
;     ...
;                     const int lrow = lrow0 + ai * 128 + m * 16; const int row = row_base + lrow;
;                     const float rs = rsqrtf(ssq[row] * (1.f / 1024.f) + EPS);
; #pragma unroll
;                     for (int bj = 0; bj < 2; ++bj) {
;                         const int c = cb + bj * 128;
;                         const f32x4 v0 = acc[ai][bj][m][0] * rs, v1 = acc[ai][bj][m][1] * rs;
;                         const float v[8] = {v0[0], v0[1], v0[2], v0[3], v1[0], v1[1], v1[2], v1[3]};
;                         if (!gate) *(v4u*)(o0 + (size_t)lrow * 9216 + u.pn * 256 + c) = pack8(v);
;                         else { float y[8];
; #pragma unroll
;                             for (int j = 0; j < 8; ++j) y[j] = silu_f(v[j]);
;                             *(v4u*)(Y + (size_t)row * 1024 + (u.pn - 36) * 256 + c) = pack8(y); }
.LBB0_145:
	v_mov_b32_e32 v127, v0
	v_lshl_add_u64 v[102:103], v[116:117], 0, v[126:127]
	global_store_dwordx4 v[102:103], v[98:101], off offset:256
	s_nop 1
	v_or_b32_e32 v100, 32, v182
	v_add_u32_e32 v106, s41, v100
	v_ashrrev_i32_e32 v107, 31, v106
	v_lshl_add_u64 v[98:99], v[106:107], 2, s[46:47]
	v_mov_b32_e32 v98, v197
	v_mad_i64_i32 v[100:101], s[2:3], v100, s13, 0
	s_mov_b64 s[2:3], -1
	v_fmamk_f32 v98, v98, 0x3a800000, v139
	v_cmp_gt_f32_e32 vcc, s33, v98
	v_mul_f32_e32 v99, 0x4b800000, v98
	s_nop 0
	v_cndmask_b32_e32 v98, v98, v99, vcc
	v_rsq_f32_e32 v98, v98
	s_nop 0
	v_mul_f32_e32 v99, 0x45800000, v98
	v_cndmask_b32_e32 v98, v98, v99, vcc
	v_pk_mul_f32 v[108:109], v[94:95], v[98:99] op_sel_hi:[1,0]
	v_lshl_add_u64 v[94:95], s[34:35], 0, v[100:101]
	v_pk_mul_f32 v[104:105], v[96:97], v[98:99] op_sel_hi:[1,0]
	v_pk_mul_f32 v[96:97], v[92:93], v[98:99] op_sel_hi:[1,0]
	v_pk_mul_f32 v[102:103], v[90:91], v[98:99] op_sel_hi:[1,0]
	s_and_b64 vcc, exec, s[4:5]
	v_lshl_add_u64 v[100:101], s[24:25], 1, v[94:95]
	s_cbranch_vccnz .LBB0_147
	v_cvt_pk_bf16_f32 v90, v108, v109
	v_cvt_pk_bf16_f32 v91, v104, v105
	v_cvt_pk_bf16_f32 v92, v102, v103
	v_cvt_pk_bf16_f32 v93, v96, v97
	v_lshl_add_u64 v[110:111], s[24:25], 1, v[94:95]
	s_mov_b64 s[2:3], 0

; __device__ __forceinline__ float silu_f(float x) { return x * __builtin_amdgcn_rcpf(1.f + __expf(-x)); }
; __device__ __forceinline__ v4u pack8(const float (&y)[8]) { return (v4u){pk2(y[0], y[1]), pk2(y[2], y[3]), pk2(y[4], y[5]), pk2(y[6], y[7])}; }
;     __device__ __forceinline__ void operator()(const f32x4 (&acc)[2][2][4][2], const pg8::Unit& u, int wr, int wc, int fr, int fq) const {
;     ...
;                     const int lrow = lrow0 + ai * 128 + m * 16; const int row = row_base + lrow;
;                     const float rs = rsqrtf(ssq[row] * (1.f / 1024.f) + EPS);
; #pragma unroll
;                     for (int bj = 0; bj < 2; ++bj) {
;                         const int c = cb + bj * 128;
;                         const f32x4 v0 = acc[ai][bj][m][0] * rs, v1 = acc[ai][bj][m][1] * rs;
;                         const float v[8] = {v0[0], v0[1], v0[2], v0[3], v1[0], v1[1], v1[2], v1[3]};
;                         if (!gate) *(v4u*)(o0 + (size_t)lrow * 9216 + u.pn * 256 + c) = pack8(v);
;                         else { float y[8];
; #pragma unroll
;                             for (int j = 0; j < 8; ++j) y[j] = silu_f(v[j]);
;                             *(v4u*)(Y + (size_t)row * 1024 + (u.pn - 36) * 256 + c) = pack8(y); }
.LBB0_153:
	v_mov_b32_e32 v127, v0
	v_lshl_add_u64 v[86:87], v[100:101], 0, v[126:127]
	global_store_dwordx4 v[86:87], v[82:85], off offset:256
	s_nop 1
	v_or_b32_e32 v84, 48, v182
	v_add_u32_e32 v90, s41, v84
	v_ashrrev_i32_e32 v91, 31, v90
	v_lshl_add_u64 v[82:83], v[90:91], 2, s[46:47]
	v_mov_b32_e32 v82, v198
	v_mad_i64_i32 v[84:85], s[2:3], v84, s13, 0
	s_mov_b64 s[2:3], -1
	v_fmamk_f32 v82, v82, 0x3a800000, v139
	v_cmp_gt_f32_e32 vcc, s33, v82
	v_mul_f32_e32 v83, 0x4b800000, v82
	s_nop 0
	v_cndmask_b32_e32 v82, v82, v83, vcc
	v_rsq_f32_e32 v82, v82
	s_nop 0
	v_mul_f32_e32 v83, 0x45800000, v82
	v_cndmask_b32_e32 v82, v82, v83, vcc
	v_pk_mul_f32 v[92:93], v[78:79], v[82:83] op_sel_hi:[1,0]
	v_lshl_add_u64 v[78:79], s[34:35], 0, v[84:85]
	v_pk_mul_f32 v[88:89], v[80:81], v[82:83] op_sel_hi:[1,0]
	v_pk_mul_f32 v[80:81], v[76:77], v[82:83] op_sel_hi:[1,0]
	v_pk_mul_f32 v[86:87], v[74:75], v[82:83] op_sel_hi:[1,0]
	s_and_b64 vcc, exec, s[4:5]
	v_lshl_add_u64 v[84:85], s[24:25], 1, v[78:79]
	s_cbranch_vccnz .LBB0_155
	v_cvt_pk_bf16_f32 v74, v92, v93
	v_cvt_pk_bf16_f32 v75, v88, v89
	v_cvt_pk_bf16_f32 v76, v86, v87
	v_cvt_pk_bf16_f32 v77, v80, v81
	v_lshl_add_u64 v[94:95], s[24:25], 1, v[78:79]
	s_mov_b64 s[2:3], 0

; __device__ __forceinline__ float silu_f(float x) { return x * __builtin_amdgcn_rcpf(1.f + __expf(-x)); }
; __device__ __forceinline__ v4u pack8(const float (&y)[8]) { return (v4u){pk2(y[0], y[1]), pk2(y[2], y[3]), pk2(y[4], y[5]), pk2(y[6], y[7])}; }
;     __device__ __forceinline__ void operator()(const f32x4 (&acc)[2][2][4][2], const pg8::Unit& u, int wr, int wc, int fr, int fq) const {
;     ...
;                     const int lrow = lrow0 + ai * 128 + m * 16; const int row = row_base + lrow;
;                     const float rs = rsqrtf(ssq[row] * (1.f / 1024.f) + EPS);
; #pragma unroll
;                     for (int bj = 0; bj < 2; ++bj) {
;                         const int c = cb + bj * 128;
;                         const f32x4 v0 = acc[ai][bj][m][0] * rs, v1 = acc[ai][bj][m][1] * rs;
;                         const float v[8] = {v0[0], v0[1], v0[2], v0[3], v1[0], v1[1], v1[2], v1[3]};
;                         if (!gate) *(v4u*)(o0 + (size_t)lrow * 9216 + u.pn * 256 + c) = pack8(v);
;                         else { float y[8];
; #pragma unroll
;                             for (int j = 0; j < 8; ++j) y[j] = silu_f(v[j]);
;                             *(v4u*)(Y + (size_t)row * 1024 + (u.pn - 36) * 256 + c) = pack8(y); }
.LBB0_161:
	v_mov_b32_e32 v127, v0
	v_lshl_add_u64 v[70:71], v[84:85], 0, v[126:127]
	global_store_dwordx4 v[70:71], v[66:69], off offset:256
	s_nop 1
	v_add_u32_e32 v68, 0x80, v182
	v_add_u32_e32 v74, s41, v68
	v_ashrrev_i32_e32 v75, 31, v74
	v_lshl_add_u64 v[66:67], v[74:75], 2, s[46:47]
	v_mov_b32_e32 v66, v199
	v_mad_i64_i32 v[68:69], s[2:3], v68, s13, 0
	s_mov_b64 s[2:3], -1
	v_fmamk_f32 v66, v66, 0x3a800000, v139
	v_cmp_gt_f32_e32 vcc, s33, v66
	v_mul_f32_e32 v67, 0x4b800000, v66
	s_nop 0
	v_cndmask_b32_e32 v66, v66, v67, vcc
	v_rsq_f32_e32 v66, v66
	s_nop 0
	v_mul_f32_e32 v67, 0x45800000, v66
	v_cndmask_b32_e32 v66, v66, v67, vcc
	v_pk_mul_f32 v[76:77], v[62:63], v[66:67] op_sel_hi:[1,0]
	v_lshl_add_u64 v[62:63], s[34:35], 0, v[68:69]
	v_pk_mul_f32 v[72:73], v[64:65], v[66:67] op_sel_hi:[1,0]
	v_pk_mul_f32 v[64:65], v[60:61], v[66:67] op_sel_hi:[1,0]
	v_pk_mul_f32 v[70:71], v[58:59], v[66:67] op_sel_hi:[1,0]
	s_and_b64 vcc, exec, s[4:5]
	v_lshl_add_u64 v[68:69], s[24:25], 1, v[62:63]
	s_cbranch_vccnz .LBB0_163
	v_cvt_pk_bf16_f32 v58, v76, v77
	v_cvt_pk_bf16_f32 v59, v72, v73
	v_cvt_pk_bf16_f32 v60, v70, v71
	v_cvt_pk_bf16_f32 v61, v64, v65
	v_lshl_add_u64 v[78:79], s[24:25], 1, v[62:63]
	s_mov_b64 s[2:3], 0

; __device__ __forceinline__ float silu_f(float x) { return x * __builtin_amdgcn_rcpf(1.f + __expf(-x)); }
; __device__ __forceinline__ v4u pack8(const float (&y)[8]) { return (v4u){pk2(y[0], y[1]), pk2(y[2], y[3]), pk2(y[4], y[5]), pk2(y[6], y[7])}; }
;     __device__ __forceinline__ void operator()(const f32x4 (&acc)[2][2][4][2], const pg8::Unit& u, int wr, int wc, int fr, int fq) const {
;     ...
;                     const int lrow = lrow0 + ai * 128 + m * 16; const int row = row_base + lrow;
;                     const float rs = rsqrtf(ssq[row] * (1.f / 1024.f) + EPS);
; #pragma unroll
;                     for (int bj = 0; bj < 2; ++bj) {
;                         const int c = cb + bj * 128;
;                         const f32x4 v0 = acc[ai][bj][m][0] * rs, v1 = acc[ai][bj][m][1] * rs;
;                         const float v[8] = {v0[0], v0[1], v0[2], v0[3], v1[0], v1[1], v1[2], v1[3]};
;                         if (!gate) *(v4u*)(o0 + (size_t)lrow * 9216 + u.pn * 256 + c) = pack8(v);
;                         else { float y[8];
; #pragma unroll
;                             for (int j = 0; j < 8; ++j) y[j] = silu_f(v[j]);
;                             *(v4u*)(Y + (size_t)row * 1024 + (u.pn - 36) * 256 + c) = pack8(y); }
.LBB0_169:
	v_mov_b32_e32 v127, v0
	v_lshl_add_u64 v[54:55], v[68:69], 0, v[126:127]
	global_store_dwordx4 v[54:55], v[50:53], off offset:256
	s_nop 1
	v_add_u32_e32 v52, 0x90, v182
	v_add_u32_e32 v58, s41, v52
	v_ashrrev_i32_e32 v59, 31, v58
	v_lshl_add_u64 v[50:51], v[58:59], 2, s[46:47]
	v_mov_b32_e32 v50, v200
	v_mad_i64_i32 v[52:53], s[2:3], v52, s13, 0
	s_mov_b64 s[2:3], -1
	v_fmamk_f32 v50, v50, 0x3a800000, v139
	v_cmp_gt_f32_e32 vcc, s33, v50
	v_mul_f32_e32 v51, 0x4b800000, v50
	s_nop 0
	v_cndmask_b32_e32 v50, v50, v51, vcc
	v_rsq_f32_e32 v50, v50
	s_nop 0
	v_mul_f32_e32 v51, 0x45800000, v50
	v_cndmask_b32_e32 v50, v50, v51, vcc
	v_pk_mul_f32 v[60:61], v[46:47], v[50:51] op_sel_hi:[1,0]
	v_lshl_add_u64 v[46:47], s[34:35], 0, v[52:53]
	v_pk_mul_f32 v[56:57], v[48:49], v[50:51] op_sel_hi:[1,0]
	v_pk_mul_f32 v[48:49], v[44:45], v[50:51] op_sel_hi:[1,0]
	v_pk_mul_f32 v[54:55], v[42:43], v[50:51] op_sel_hi:[1,0]
	s_and_b64 vcc, exec, s[4:5]
	v_lshl_add_u64 v[52:53], s[24:25], 1, v[46:47]
	s_cbranch_vccnz .LBB0_171
	v_cvt_pk_bf16_f32 v42, v60, v61
	v_cvt_pk_bf16_f32 v43, v56, v57
	v_cvt_pk_bf16_f32 v44, v54, v55
	v_cvt_pk_bf16_f32 v45, v48, v49
	v_lshl_add_u64 v[62:63], s[24:25], 1, v[46:47]
	s_mov_b64 s[2:3], 0

; __device__ __forceinline__ float silu_f(float x) { return x * __builtin_amdgcn_rcpf(1.f + __expf(-x)); }
; __device__ __forceinline__ v4u pack8(const float (&y)[8]) { return (v4u){pk2(y[0], y[1]), pk2(y[2], y[3]), pk2(y[4], y[5]), pk2(y[6], y[7])}; }
;     __device__ __forceinline__ void operator()(const f32x4 (&acc)[2][2][4][2], const pg8::Unit& u, int wr, int wc, int fr, int fq) const {
;     ...
;                     const int lrow = lrow0 + ai * 128 + m * 16; const int row = row_base + lrow;
;                     const float rs = rsqrtf(ssq[row] * (1.f / 1024.f) + EPS);
; #pragma unroll
;                     for (int bj = 0; bj < 2; ++bj) {
;                         const int c = cb + bj * 128;
;                         const f32x4 v0 = acc[ai][bj][m][0] * rs, v1 = acc[ai][bj][m][1] * rs;
;                         const float v[8] = {v0[0], v0[1], v0[2], v0[3], v1[0], v1[1], v1[2], v1[3]};
;                         if (!gate) *(v4u*)(o0 + (size_t)lrow * 9216 + u.pn * 256 + c) = pack8(v);
;                         else { float y[8];
; #pragma unroll
;                             for (int j = 0; j < 8; ++j) y[j] = silu_f(v[j]);
;                             *(v4u*)(Y + (size_t)row * 1024 + (u.pn - 36) * 256 + c) = pack8(y); }
.LBB0_177:
	v_mov_b32_e32 v127, v0
	v_lshl_add_u64 v[38:39], v[52:53], 0, v[126:127]
	global_store_dwordx4 v[38:39], v[34:37], off offset:256
	s_nop 1
	v_add_u32_e32 v36, 0xa0, v182
	v_add_u32_e32 v42, s41, v36
	v_ashrrev_i32_e32 v43, 31, v42
	v_lshl_add_u64 v[34:35], v[42:43], 2, s[46:47]
	v_mov_b32_e32 v34, v201
	v_mad_i64_i32 v[36:37], s[2:3], v36, s13, 0
	s_mov_b64 s[2:3], -1
	v_fmamk_f32 v34, v34, 0x3a800000, v139
	v_cmp_gt_f32_e32 vcc, s33, v34
	v_mul_f32_e32 v35, 0x4b800000, v34
	s_nop 0
	v_cndmask_b32_e32 v34, v34, v35, vcc
	v_rsq_f32_e32 v34, v34
	s_nop 0
	v_mul_f32_e32 v35, 0x45800000, v34
	v_cndmask_b32_e32 v34, v34, v35, vcc
	v_pk_mul_f32 v[44:45], v[30:31], v[34:35] op_sel_hi:[1,0]
	v_lshl_add_u64 v[30:31], s[34:35], 0, v[36:37]
	v_pk_mul_f32 v[40:41], v[32:33], v[34:35] op_sel_hi:[1,0]
	v_pk_mul_f32 v[32:33], v[28:29], v[34:35] op_sel_hi:[1,0]
	v_pk_mul_f32 v[38:39], v[26:27], v[34:35] op_sel_hi:[1,0]
	s_and_b64 vcc, exec, s[4:5]
	v_lshl_add_u64 v[36:37], s[24:25], 1, v[30:31]
	s_cbranch_vccnz .LBB0_179
	v_cvt_pk_bf16_f32 v26, v44, v45
	v_cvt_pk_bf16_f32 v27, v40, v41
	v_cvt_pk_bf16_f32 v28, v38, v39
	v_cvt_pk_bf16_f32 v29, v32, v33
	v_lshl_add_u64 v[46:47], s[24:25], 1, v[30:31]
	s_mov_b64 s[2:3], 0

; __device__ __forceinline__ float silu_f(float x) { return x * __builtin_amdgcn_rcpf(1.f + __expf(-x)); }
; __device__ __forceinline__ v4u pack8(const float (&y)[8]) { return (v4u){pk2(y[0], y[1]), pk2(y[2], y[3]), pk2(y[4], y[5]), pk2(y[6], y[7])}; }
;     __device__ __forceinline__ void operator()(const f32x4 (&acc)[2][2][4][2], const pg8::Unit& u, int wr, int wc, int fr, int fq) const {
;     ...
;                     const int lrow = lrow0 + ai * 128 + m * 16; const int row = row_base + lrow;
;                     const float rs = rsqrtf(ssq[row] * (1.f / 1024.f) + EPS);
; #pragma unroll
;                     for (int bj = 0; bj < 2; ++bj) {
;                         const int c = cb + bj * 128;
;                         const f32x4 v0 = acc[ai][bj][m][0] * rs, v1 = acc[ai][bj][m][1] * rs;
;                         const float v[8] = {v0[0], v0[1], v0[2], v0[3], v1[0], v1[1], v1[2], v1[3]};
;                         if (!gate) *(v4u*)(o0 + (size_t)lrow * 9216 + u.pn * 256 + c) = pack8(v);
;                         else { float y[8];
; #pragma unroll
;                             for (int j = 0; j < 8; ++j) y[j] = silu_f(v[j]);
;                             *(v4u*)(Y + (size_t)row * 1024 + (u.pn - 36) * 256 + c) = pack8(y); }
.LBB0_185:
	v_mov_b32_e32 v127, v0
	v_lshl_add_u64 v[22:23], v[36:37], 0, v[126:127]
	global_store_dwordx4 v[22:23], v[18:21], off offset:256
	s_nop 1
	v_add_u32_e32 v20, 0xb0, v182
	v_add_u32_e32 v26, s41, v20
	v_ashrrev_i32_e32 v27, 31, v26
	v_lshl_add_u64 v[18:19], v[26:27], 2, s[46:47]
	v_mov_b32_e32 v18, v202
	v_mad_i64_i32 v[20:21], s[2:3], v20, s13, 0
	s_mov_b64 s[2:3], -1
	v_fmamk_f32 v18, v18, 0x3a800000, v139
	v_cmp_gt_f32_e32 vcc, s33, v18
	v_mul_f32_e32 v19, 0x4b800000, v18
	s_nop 0
	v_cndmask_b32_e32 v18, v18, v19, vcc
	v_rsq_f32_e32 v18, v18
	s_nop 0
	v_mul_f32_e32 v19, 0x45800000, v18
	v_cndmask_b32_e32 v18, v18, v19, vcc
	v_pk_mul_f32 v[28:29], v[14:15], v[18:19] op_sel_hi:[1,0]
	v_lshl_add_u64 v[14:15], s[34:35], 0, v[20:21]
	v_pk_mul_f32 v[24:25], v[16:17], v[18:19] op_sel_hi:[1,0]
	v_pk_mul_f32 v[16:17], v[12:13], v[18:19] op_sel_hi:[1,0]
	v_pk_mul_f32 v[22:23], v[10:11], v[18:19] op_sel_hi:[1,0]
	s_and_b64 vcc, exec, s[4:5]
	v_lshl_add_u64 v[20:21], s[24:25], 1, v[14:15]
	s_cbranch_vccnz .LBB0_187
	v_cvt_pk_bf16_f32 v10, v28, v29
	v_cvt_pk_bf16_f32 v11, v24, v25
	v_cvt_pk_bf16_f32 v12, v22, v23
	v_cvt_pk_bf16_f32 v13, v16, v17
	v_lshl_add_u64 v[30:31], s[24:25], 1, v[14:15]
	s_mov_b64 s[2:3], 0
